# rownorm/finalnorm row loads: sc1 nt (agent scope + streaming) instead of nt
# speedup vs baseline: 1.0098x; 1.0015x over previous
.LBB0_49:
	v_lshrrev_b32_e32 v1, 3, v2
	v_and_b32_e32 v0, 0x700, v80
	v_and_b32_e32 v1, 0xf8, v1
	v_and_b32_e32 v3, 0xfffff807, v2
	v_or3_b32 v0, v0, v3, v1
	v_cndmask_b32_e32 v0, v2, v0, vcc
	v_ashrrev_i32_e32 v1, 31, v0
	v_lshlrev_b64 v[4:5], 12, v[0:1]
	v_lshl_add_u64 v[4:5], v[66:67], 0, v[4:5]
	s_waitcnt lgkmcnt(0)
	global_load_dwordx4 v[48:51], v[4:5], off sc1 nt
	global_load_dwordx4 v[52:55], v[4:5], off offset:1024 sc1 nt
	global_load_dwordx4 v[56:59], v[4:5], off offset:2048 sc1 nt
	global_load_dwordx4 v[60:63], v[4:5], off offset:3072 sc1 nt
	v_add_u32_e32 v3, s18, v2
	v_cmp_gt_i32_e64 s[6:7], s3, v3
	v_lshlrev_b64 v[0:1], 11, v[0:1]
	s_waitcnt vmcnt(1)
	v_mov_b32_e32 v84, v57
	v_cndmask_b32_e64 v4, v2, v3, s[6:7]
	v_lshlrev_b32_e32 v5, 5, v4
	v_lshrrev_b32_e32 v6, 3, v4
	v_and_b32_e32 v7, 0xfffff807, v4
	v_and_b32_e32 v5, 0x700, v5
	v_and_b32_e32 v6, 0xf8, v6
	v_or3_b32 v5, v5, v7, v6
	v_cndmask_b32_e32 v72, v4, v5, vcc
	v_ashrrev_i32_e32 v73, 31, v72
	v_lshlrev_b64 v[4:5], 12, v[72:73]
	v_lshl_add_u64 v[4:5], v[66:67], 0, v[4:5]
	global_load_dwordx4 v[16:19], v[4:5], off offset:1024 sc1 nt
	global_load_dwordx4 v[32:35], v[4:5], off sc1 nt
	global_load_dwordx4 v[20:23], v[4:5], off offset:2048 sc1 nt
	v_add_u32_e32 v3, s18, v3
	v_cmp_gt_i32_e64 s[8:9], s3, v3
	global_load_dwordx4 v[12:15], v[4:5], off offset:3072 sc1 nt
	v_add_u32_e32 v82, s18, v3
	v_cndmask_b32_e64 v4, v2, v3, s[8:9]
	v_lshlrev_b32_e32 v3, 5, v4
	v_lshrrev_b32_e32 v5, 3, v4
	v_cmp_gt_i32_e64 s[4:5], s3, v82
	v_and_b32_e32 v6, 0xfffff807, v4
	v_and_b32_e32 v3, 0x700, v3
	v_cndmask_b32_e64 v2, v2, v82, s[4:5]
	v_and_b32_e32 v5, 0xf8, v5
	v_lshlrev_b32_e32 v7, 5, v2
	v_lshrrev_b32_e32 v8, 3, v2
	v_or3_b32 v3, v3, v6, v5
	v_and_b32_e32 v9, 0xfffff807, v2
	v_and_b32_e32 v5, 0x700, v7
	v_and_b32_e32 v6, 0xf8, v8
	v_cndmask_b32_e32 v70, v4, v3, vcc
	v_or3_b32 v3, v5, v9, v6
	v_ashrrev_i32_e32 v71, 31, v70
	v_cndmask_b32_e32 v68, v2, v3, vcc
	v_lshlrev_b64 v[2:3], 12, v[70:71]
	v_mov_b32_e32 v8, v49
	v_mov_b32_e32 v9, v53
	v_lshl_add_u64 v[2:3], v[66:67], 0, v[2:3]
	v_mov_b32_e32 v6, v48
	v_mov_b32_e32 v7, v52
	s_waitcnt vmcnt(4)
	v_mov_b32_e32 v85, v61
	v_pk_mul_f32 v[8:9], v[8:9], v[8:9]
	global_load_dwordx4 v[44:47], v[2:3], off sc1 nt
	global_load_dwordx4 v[36:39], v[2:3], off offset:1024 sc1 nt
	global_load_dwordx4 v[40:43], v[2:3], off offset:2048 sc1 nt
	global_load_dwordx4 v[28:31], v[2:3], off offset:3072 sc1 nt
	v_mov_b32_e32 v2, v50
	v_mov_b32_e32 v3, v54
	v_mov_b32_e32 v26, v56
	v_mov_b32_e32 v27, v60
	v_pk_mul_f32 v[84:85], v[84:85], v[84:85]
	v_pk_fma_f32 v[6:7], v[6:7], v[6:7], v[8:9]
	v_mov_b32_e32 v4, v51
	v_mov_b32_e32 v5, v55
	v_mov_b32_e32 v10, v58
	v_mov_b32_e32 v11, v62
	v_pk_fma_f32 v[8:9], v[26:27], v[26:27], v[84:85]
	v_pk_fma_f32 v[2:3], v[2:3], v[2:3], v[6:7]
	v_mov_b32_e32 v24, v59
	v_mov_b32_e32 v25, v63
	v_pk_fma_f32 v[6:7], v[10:11], v[10:11], v[8:9]
	v_pk_fma_f32 v[2:3], v[4:5], v[4:5], v[2:3]
	v_pk_fma_f32 v[4:5], v[24:25], v[24:25], v[6:7]
	v_add_f32_e32 v2, v2, v3
	v_add_f32_e32 v2, v2, v4
	v_add_f32_e32 v8, v2, v5
	ds_bpermute_b32 v9, v74, v8
	v_ashrrev_i32_e32 v69, 31, v68
	v_lshlrev_b64 v[2:3], 12, v[68:69]
	v_lshl_add_u64 v[2:3], v[66:67], 0, v[2:3]
	global_load_dwordx4 v[4:7], v[2:3], off offset:1024 sc1 nt
	global_load_dwordx4 v[24:27], v[2:3], off sc1 nt
	s_waitcnt lgkmcnt(0)
	v_add_f32_e32 v8, v8, v9
	ds_bpermute_b32 v9, v75, v8
	v_lshl_add_u64 v[84:85], v[64:65], 0, v[0:1]
	s_waitcnt lgkmcnt(0)
	v_add_f32_e32 v83, v8, v9
	global_load_dwordx4 v[8:11], v[2:3], off offset:2048 sc1 nt
	s_nop 0
	global_load_dwordx4 v[0:3], v[2:3], off offset:3072 sc1 nt
	ds_bpermute_b32 v88, v76, v83
	s_waitcnt lgkmcnt(0)
	v_add_f32_e32 v83, v83, v88
	ds_bpermute_b32 v96, v77, v83
	s_waitcnt lgkmcnt(0)
	v_add_f32_e32 v83, v83, v96
	ds_bpermute_b32 v100, v78, v83
	s_waitcnt vmcnt(11)
	v_pk_mul_f32 v[86:87], v[16:17], v[16:17]
	s_waitcnt vmcnt(10)
	v_pk_mul_f32 v[90:91], v[32:33], v[32:33]
	v_add_f32_e32 v86, v86, v87
	v_add_f32_e32 v87, v90, v91
	s_waitcnt lgkmcnt(0)
	v_add_f32_e32 v83, v83, v100
	ds_bpermute_b32 v90, v79, v83
	v_pk_mul_f32 v[88:89], v[18:19], v[18:19]
	v_pk_mul_f32 v[92:93], v[34:35], v[34:35]
	v_add_f32_e32 v86, v86, v88
	s_waitcnt vmcnt(9)
	v_pk_mul_f32 v[94:95], v[20:21], v[20:21]
	s_waitcnt lgkmcnt(0)
	v_add_f32_e32 v83, v83, v90
	v_fmamk_f32 v83, v83, 0x3a800000, v81
	v_mul_f32_e32 v90, 0x4b800000, v83
	v_cmp_gt_f32_e64 s[10:11], s22, v83
	v_add_f32_e32 v87, v87, v92
	v_pk_mul_f32 v[96:97], v[22:23], v[22:23]
	v_cndmask_b32_e64 v83, v83, v90, s[10:11]
	v_rsq_f32_e32 v83, v83
	v_add_f32_e32 v90, v86, v89
	s_waitcnt vmcnt(8)
	v_pk_mul_f32 v[98:99], v[12:13], v[12:13]
	v_add_f32_e32 v91, v94, v95
	v_mul_f32_e32 v86, 0x45800000, v83
	v_cndmask_b32_e64 v86, v83, v86, s[10:11]
	v_pk_mul_f32 v[48:49], v[48:49], v[86:87] op_sel_hi:[1,0]
	v_pk_mul_f32 v[50:51], v[50:51], v[86:87] op_sel_hi:[1,0]
	v_add_f32_e32 v88, v91, v96
	v_add_f32_e32 v91, v87, v93
	v_pk_mul_f32 v[52:53], v[52:53], v[86:87] op_sel_hi:[1,0]
	v_pk_mul_f32 v[54:55], v[54:55], v[86:87] op_sel_hi:[1,0]
	v_pk_mul_f32 v[56:57], v[56:57], v[86:87] op_sel_hi:[1,0]
	v_pk_mul_f32 v[58:59], v[58:59], v[86:87] op_sel_hi:[1,0]
	v_pk_mul_f32 v[60:61], v[60:61], v[86:87] op_sel_hi:[1,0]
	v_pk_mul_f32 v[62:63], v[62:63], v[86:87] op_sel_hi:[1,0]
	v_cvt_pk_bf16_f32 v86, v48, v49
	v_cvt_pk_bf16_f32 v87, v50, v51
	v_add_f32_e32 v50, v98, v99
	v_pk_mul_f32 v[48:49], v[14:15], v[14:15]
	v_add_f32_e32 v92, v88, v97
	v_add_f32_e32 v48, v50, v48
	v_add_f32_e32 v50, v48, v49
	s_waitcnt vmcnt(6)
	v_pk_mul_f32 v[48:49], v[36:37], v[36:37]
	v_cvt_pk_bf16_f32 v88, v52, v53
	v_add_f32_e32 v51, v48, v49
	v_pk_mul_f32 v[48:49], v[38:39], v[38:39]
	v_cvt_pk_bf16_f32 v89, v54, v55
	v_add_f32_e32 v48, v51, v48
	v_add_f32_e32 v51, v48, v49
	v_pk_mul_f32 v[48:49], v[44:45], v[44:45]
	v_cvt_pk_bf16_f32 v54, v56, v57
	v_add_f32_e32 v52, v48, v49
	v_pk_mul_f32 v[48:49], v[46:47], v[46:47]
	v_cvt_pk_bf16_f32 v55, v58, v59
	v_add_f32_e32 v48, v52, v48
	v_add_f32_e32 v52, v48, v49
	s_waitcnt vmcnt(5)
	v_pk_mul_f32 v[48:49], v[40:41], v[40:41]
	s_nop 0
	v_add_f32_e32 v53, v48, v49
	v_pk_mul_f32 v[48:49], v[42:43], v[42:43]
	s_nop 0
	v_add_f32_e32 v48, v53, v48
	v_add_f32_e32 v53, v48, v49
	s_waitcnt vmcnt(4)
	v_pk_mul_f32 v[48:49], v[28:29], v[28:29]
	s_nop 0
	v_add_f32_e32 v56, v48, v49
	v_pk_mul_f32 v[48:49], v[30:31], v[30:31]
	s_nop 0
	v_add_f32_e32 v48, v56, v48
	v_add_f32_e32 v56, v48, v49
	s_waitcnt vmcnt(3)
	v_pk_mul_f32 v[48:49], v[4:5], v[4:5]
	s_nop 0
	v_add_f32_e32 v57, v48, v49
	v_pk_mul_f32 v[48:49], v[6:7], v[6:7]
	s_nop 0
	v_add_f32_e32 v48, v57, v48
	v_add_f32_e32 v57, v48, v49
	s_waitcnt vmcnt(2)
	v_pk_mul_f32 v[48:49], v[24:25], v[24:25]
	s_nop 0
	v_add_f32_e32 v58, v48, v49
	v_pk_mul_f32 v[48:49], v[26:27], v[26:27]
	s_nop 0
	v_add_f32_e32 v48, v58, v48
	v_add_f32_e32 v58, v48, v49
	s_waitcnt vmcnt(1)
	v_pk_mul_f32 v[48:49], v[8:9], v[8:9]
	s_nop 0
	v_add_f32_e32 v59, v48, v49
	v_pk_mul_f32 v[48:49], v[10:11], v[10:11]
	s_nop 0
	v_add_f32_e32 v48, v59, v48
	v_add_f32_e32 v59, v48, v49
	s_waitcnt vmcnt(0)
	v_pk_mul_f32 v[48:49], v[0:1], v[0:1]
	s_nop 0
	v_add_f32_e32 v83, v48, v49
	v_pk_mul_f32 v[48:49], v[2:3], v[2:3]
	s_nop 0
	v_add_f32_e32 v48, v83, v48
	v_add_f32_e32 v48, v48, v49
	v_add_f32_e32 v49, v91, v90
	v_add_f32_e32 v49, v49, v92
	v_add_f32_e32 v49, v49, v50
	v_add_f32_e32 v50, v52, v51
	v_add_f32_e32 v51, v58, v57
	v_add_f32_e32 v50, v50, v53
	v_add_f32_e32 v51, v51, v59
	v_add_f32_e32 v50, v50, v56
	v_add_f32_e32 v48, v51, v48
	ds_bpermute_b32 v52, v74, v49
	ds_bpermute_b32 v53, v74, v50
	ds_bpermute_b32 v51, v74, v48
	v_cvt_pk_bf16_f32 v56, v60, v61
	v_cvt_pk_bf16_f32 v57, v62, v63
	s_waitcnt lgkmcnt(2)
	v_add_f32_e32 v49, v49, v52
	s_waitcnt lgkmcnt(1)
	v_add_f32_e32 v50, v50, v53
	s_waitcnt lgkmcnt(0)
	v_add_f32_e32 v48, v48, v51
	ds_bpermute_b32 v52, v75, v49
	ds_bpermute_b32 v53, v75, v50
	ds_bpermute_b32 v51, v75, v48
	global_store_dwordx2 v[84:85], v[86:87], off
	global_store_dwordx2 v[84:85], v[88:89], off offset:512
	global_store_dwordx2 v[84:85], v[54:55], off offset:1024
	global_store_dwordx2 v[84:85], v[56:57], off offset:1536
	s_waitcnt lgkmcnt(2)
	v_add_f32_e32 v49, v49, v52
	s_waitcnt lgkmcnt(1)
	v_add_f32_e32 v50, v50, v53
	s_waitcnt lgkmcnt(0)
	v_add_f32_e32 v48, v48, v51
	ds_bpermute_b32 v52, v76, v49
	ds_bpermute_b32 v53, v76, v50
	ds_bpermute_b32 v51, v76, v48
	s_waitcnt lgkmcnt(2)
	v_add_f32_e32 v49, v49, v52
	s_waitcnt lgkmcnt(1)
	v_add_f32_e32 v50, v50, v53
	s_waitcnt lgkmcnt(0)
	v_add_f32_e32 v48, v48, v51
	ds_bpermute_b32 v52, v77, v49
	ds_bpermute_b32 v53, v77, v50
	ds_bpermute_b32 v51, v77, v48
	s_waitcnt lgkmcnt(2)
	v_add_f32_e32 v49, v49, v52
	s_waitcnt lgkmcnt(1)
	v_add_f32_e32 v50, v50, v53
	s_waitcnt lgkmcnt(0)
	v_add_f32_e32 v48, v48, v51
	ds_bpermute_b32 v52, v78, v49
	ds_bpermute_b32 v53, v78, v50
	ds_bpermute_b32 v51, v78, v48
	s_waitcnt lgkmcnt(2)
	v_add_f32_e32 v52, v49, v52
	s_waitcnt lgkmcnt(1)
	v_add_f32_e32 v50, v50, v53
	s_waitcnt lgkmcnt(0)
	v_add_f32_e32 v48, v48, v51
	ds_bpermute_b32 v53, v79, v52
	ds_bpermute_b32 v51, v79, v50
	ds_bpermute_b32 v49, v79, v48
	s_and_saveexec_b64 s[10:11], s[6:7]
	s_cbranch_execnz .LBB0_52
	s_or_b64 exec, exec, s[10:11]
	s_and_saveexec_b64 s[10:11], s[8:9]
	s_cbranch_execnz .LBB0_53

.LBB0_388:
	v_add_u32_e32 v0, s18, v58
	v_cmp_gt_i32_e64 s[8:9], s3, v0
	v_lshrrev_b32_e32 v69, 3, v58
	v_and_b32_e32 v59, 0x700, v66
	v_cndmask_b32_e64 v1, v58, v0, s[8:9]
	v_lshlrev_b32_e32 v2, 5, v1
	v_lshrrev_b32_e32 v3, 3, v1
	v_and_b32_e32 v2, 0x700, v2
	v_and_b32_e32 v3, 0xf8, v3
	v_and_b32_e32 v4, 0xfffff807, v1
	v_or3_b32 v2, v2, v4, v3
	v_cndmask_b32_e32 v56, v1, v2, vcc
	v_add_u32_e32 v2, s18, v0
	v_cmp_gt_i32_e64 s[4:5], s3, v2
	v_ashrrev_i32_e32 v57, 31, v56
	v_add_u32_e32 v68, s18, v2
	v_cndmask_b32_e64 v3, v58, v2, s[4:5]
	v_lshlrev_b32_e32 v0, 5, v3
	v_and_b32_e32 v4, 0x700, v0
	v_lshlrev_b64 v[0:1], 12, v[56:57]
	v_lshl_add_u64 v[0:1], v[50:51], 0, v[0:1]
	v_lshrrev_b32_e32 v5, 3, v3
	global_load_dwordx4 v[44:47], v[0:1], off sc1 nt
	global_load_dwordx4 v[40:43], v[0:1], off offset:1024 sc1 nt
	v_and_b32_e32 v5, 0xf8, v5
	v_and_b32_e32 v6, 0xfffff807, v3
	global_load_dwordx4 v[36:39], v[0:1], off offset:2048 sc1 nt
	global_load_dwordx4 v[32:35], v[0:1], off offset:3072 sc1 nt
	v_or3_b32 v0, v4, v6, v5
	v_cndmask_b32_e32 v54, v3, v0, vcc
	v_ashrrev_i32_e32 v55, 31, v54
	v_lshlrev_b64 v[0:1], 12, v[54:55]
	v_lshl_add_u64 v[0:1], v[50:51], 0, v[0:1]
	v_cmp_gt_i32_e64 s[6:7], s3, v68
	global_load_dwordx4 v[28:31], v[0:1], off sc1 nt
	global_load_dwordx4 v[24:27], v[0:1], off offset:1024 sc1 nt
	global_load_dwordx4 v[20:23], v[0:1], off offset:2048 sc1 nt
	global_load_dwordx4 v[16:19], v[0:1], off offset:3072 sc1 nt
	v_cndmask_b32_e64 v0, v58, v68, s[6:7]
	v_lshlrev_b32_e32 v1, 5, v0
	v_lshrrev_b32_e32 v2, 3, v0
	v_and_b32_e32 v3, 0xfffff807, v0
	v_and_b32_e32 v1, 0x700, v1
	v_and_b32_e32 v2, 0xf8, v2
	v_or3_b32 v1, v1, v3, v2
	v_cndmask_b32_e32 v52, v0, v1, vcc
	v_ashrrev_i32_e32 v53, 31, v52
	v_lshlrev_b64 v[0:1], 12, v[52:53]
	v_lshl_add_u64 v[0:1], v[50:51], 0, v[0:1]
	global_load_dwordx4 v[12:15], v[0:1], off sc1 nt
	global_load_dwordx4 v[8:11], v[0:1], off offset:1024 sc1 nt
	global_load_dwordx4 v[4:7], v[0:1], off offset:2048 sc1 nt
	s_nop 0
	global_load_dwordx4 v[0:3], v[0:1], off offset:3072 sc1 nt
	s_waitcnt lgkmcnt(0)
	v_and_b32_e32 v70, 0xfffff807, v58
	v_and_b32_e32 v69, 0xf8, v69
	v_or3_b32 v59, v59, v70, v69
	v_cndmask_b32_e32 v58, v58, v59, vcc
	v_ashrrev_i32_e32 v59, 31, v58
	v_lshlrev_b64 v[70:71], 12, v[58:59]
	v_lshl_add_u64 v[70:71], v[50:51], 0, v[70:71]
	global_load_dwordx4 v[76:79], v[70:71], off sc1 nt
	global_load_dwordx4 v[80:83], v[70:71], off offset:1024 sc1 nt
	global_load_dwordx4 v[84:87], v[70:71], off offset:2048 sc1 nt
	global_load_dwordx4 v[88:91], v[70:71], off offset:3072 sc1 nt
	v_lshlrev_b64 v[58:59], 11, v[58:59]
	v_lshl_add_u64 v[58:59], v[48:49], 0, v[58:59]
	s_waitcnt vmcnt(15)
	v_pk_mul_f32 v[70:71], v[44:45], v[44:45]
	s_waitcnt vmcnt(14)
	v_pk_mul_f32 v[74:75], v[40:41], v[40:41]
	v_pk_mul_f32 v[72:73], v[46:47], v[46:47]
	v_pk_mul_f32 v[92:93], v[42:43], v[42:43]
	s_waitcnt vmcnt(13)
	v_pk_mul_f32 v[94:95], v[36:37], v[36:37]
	v_add_f32_e32 v69, v74, v75
	v_add_f32_e32 v110, v70, v71
	v_pk_mul_f32 v[96:97], v[38:39], v[38:39]
	s_waitcnt vmcnt(12)
	v_pk_mul_f32 v[98:99], v[32:33], v[32:33]
	v_add_f32_e32 v111, v94, v95
	v_add_f32_e32 v69, v69, v92
	v_add_f32_e32 v72, v110, v72
	v_pk_mul_f32 v[100:101], v[34:35], v[34:35]
	v_add_f32_e32 v112, v98, v99
	v_add_f32_e32 v92, v111, v96
	v_add_f32_e32 v69, v69, v93
	v_add_f32_e32 v72, v72, v73
	v_add_f32_e32 v96, v112, v100
	v_add_f32_e32 v73, v92, v97
	v_add_f32_e32 v69, v72, v69
	v_add_f32_e32 v92, v96, v101
	v_add_f32_e32 v69, v69, v73
	s_waitcnt vmcnt(11)
	v_pk_mul_f32 v[70:71], v[28:29], v[28:29]
	s_waitcnt vmcnt(9)
	v_pk_mul_f32 v[102:103], v[20:21], v[20:21]
	v_add_f32_e32 v69, v69, v92
	v_add_f32_e32 v70, v70, v71
	v_add_f32_e32 v71, v102, v103
	ds_bpermute_b32 v103, v60, v69
	v_pk_mul_f32 v[74:75], v[30:31], v[30:31]
	v_pk_mul_f32 v[94:95], v[24:25], v[24:25]
	v_pk_mul_f32 v[98:99], v[26:27], v[26:27]
	v_add_f32_e32 v94, v94, v95
	v_add_f32_e32 v70, v70, v74
	v_pk_mul_f32 v[104:105], v[22:23], v[22:23]
	v_add_f32_e32 v72, v94, v98
	v_add_f32_e32 v70, v70, v75
	s_waitcnt vmcnt(6)
	v_pk_mul_f32 v[74:75], v[8:9], v[8:9]
	s_waitcnt lgkmcnt(0)
	v_add_f32_e32 v69, v69, v103
	v_add_f32_e32 v72, v72, v99
	v_add_f32_e32 v71, v71, v104
	v_add_f32_e32 v74, v74, v75
	ds_bpermute_b32 v75, v61, v69
	v_pk_mul_f32 v[106:107], v[16:17], v[16:17]
	v_add_f32_e32 v70, v70, v72
	v_add_f32_e32 v71, v71, v105
	v_pk_mul_f32 v[108:109], v[18:19], v[18:19]
	v_add_f32_e32 v70, v70, v71
	v_add_f32_e32 v71, v106, v107
	v_add_f32_e32 v71, v71, v108
	v_add_f32_e32 v71, v71, v109
	v_add_f32_e32 v102, v70, v71
	v_pk_mul_f32 v[70:71], v[12:13], v[12:13]
	s_waitcnt lgkmcnt(0)
	v_add_f32_e32 v69, v69, v75
	v_add_f32_e32 v70, v70, v71
	ds_bpermute_b32 v71, v62, v69
	v_pk_mul_f32 v[72:73], v[14:15], v[14:15]
	v_pk_mul_f32 v[92:93], v[10:11], v[10:11]
	s_waitcnt vmcnt(5)
	v_pk_mul_f32 v[94:95], v[4:5], v[4:5]
	v_pk_mul_f32 v[96:97], v[6:7], v[6:7]
	s_waitcnt lgkmcnt(0)
	v_add_f32_e32 v69, v69, v71
	v_add_f32_e32 v74, v74, v92
	v_add_f32_e32 v70, v70, v72
	v_add_f32_e32 v72, v94, v95
	ds_bpermute_b32 v71, v63, v69
	v_add_f32_e32 v74, v74, v93
	v_add_f32_e32 v70, v70, v73
	v_add_f32_e32 v72, v72, v96
	s_waitcnt vmcnt(4)
	v_pk_mul_f32 v[98:99], v[0:1], v[0:1]
	v_add_f32_e32 v70, v70, v74
	v_add_f32_e32 v72, v72, v97
	v_pk_mul_f32 v[100:101], v[2:3], v[2:3]
	v_add_f32_e32 v96, v70, v72
	v_add_f32_e32 v70, v98, v99
	s_waitcnt vmcnt(3)
	v_mov_b32_e32 v92, v77
	s_waitcnt vmcnt(2)
	v_mov_b32_e32 v93, v81
	v_add_f32_e32 v70, v70, v100
	v_mov_b32_e32 v74, v76
	v_mov_b32_e32 v75, v80
	v_pk_mul_f32 v[92:93], v[92:93], v[92:93]
	v_add_f32_e32 v97, v70, v101
	s_waitcnt lgkmcnt(0)
	v_add_f32_e32 v69, v69, v71
	v_mov_b32_e32 v70, v78
	v_mov_b32_e32 v71, v82
	v_pk_fma_f32 v[74:75], v[74:75], v[74:75], v[92:93]
	s_waitcnt vmcnt(1)
	v_mov_b32_e32 v94, v85
	s_waitcnt vmcnt(0)
	v_mov_b32_e32 v95, v89
	v_mov_b32_e32 v72, v79
	v_mov_b32_e32 v73, v83
	v_pk_fma_f32 v[70:71], v[70:71], v[70:71], v[74:75]
	v_mov_b32_e32 v92, v84
	v_mov_b32_e32 v93, v88
	v_pk_mul_f32 v[94:95], v[94:95], v[94:95]
	v_pk_fma_f32 v[70:71], v[72:73], v[72:73], v[70:71]
	v_mov_b32_e32 v72, v86
	v_mov_b32_e32 v73, v90
	v_pk_fma_f32 v[92:93], v[92:93], v[92:93], v[94:95]
	v_mov_b32_e32 v74, v87
	v_mov_b32_e32 v75, v91
	v_pk_fma_f32 v[72:73], v[72:73], v[72:73], v[92:93]
	v_add_f32_e32 v70, v70, v71
	v_pk_fma_f32 v[72:73], v[74:75], v[74:75], v[72:73]
	ds_bpermute_b32 v74, v60, v102
	v_add_f32_e32 v70, v70, v72
	v_add_f32_e32 v70, v70, v73
	ds_bpermute_b32 v71, v60, v70
	ds_bpermute_b32 v98, v64, v69
	s_waitcnt lgkmcnt(2)
	v_add_f32_e32 v74, v102, v74
	ds_bpermute_b32 v75, v61, v74
	v_add_f32_e32 v72, v96, v97
	s_waitcnt lgkmcnt(2)
	v_add_f32_e32 v70, v70, v71
	ds_bpermute_b32 v71, v61, v70
	s_waitcnt lgkmcnt(2)
	v_add_f32_e32 v73, v69, v98
	ds_bpermute_b32 v69, v60, v72
	s_waitcnt lgkmcnt(2)
	v_add_f32_e32 v74, v74, v75
	ds_bpermute_b32 v75, v62, v74
	s_waitcnt lgkmcnt(2)
	v_add_f32_e32 v70, v70, v71
	ds_bpermute_b32 v71, v62, v70
	s_waitcnt lgkmcnt(2)
	v_add_f32_e32 v69, v72, v69
	ds_bpermute_b32 v72, v61, v69
	s_waitcnt lgkmcnt(2)
	v_add_f32_e32 v74, v74, v75
	ds_bpermute_b32 v75, v63, v74
	s_waitcnt lgkmcnt(2)
	v_add_f32_e32 v70, v70, v71
	ds_bpermute_b32 v71, v63, v70
	s_waitcnt lgkmcnt(2)
	v_add_f32_e32 v69, v69, v72
	ds_bpermute_b32 v72, v62, v69
	s_waitcnt lgkmcnt(2)
	v_add_f32_e32 v75, v74, v75
	ds_bpermute_b32 v92, v64, v75
	s_waitcnt lgkmcnt(2)
	v_add_f32_e32 v70, v70, v71
	ds_bpermute_b32 v71, v64, v70
	s_waitcnt lgkmcnt(2)
	v_add_f32_e32 v69, v69, v72
	ds_bpermute_b32 v72, v63, v69
	ds_bpermute_b32 v74, v65, v73
	s_waitcnt lgkmcnt(2)
	v_add_f32_e32 v70, v70, v71
	ds_bpermute_b32 v94, v65, v70
	v_add_f32_e32 v71, v75, v92
	s_waitcnt lgkmcnt(2)
	v_add_f32_e32 v69, v69, v72
	ds_bpermute_b32 v93, v64, v69
	ds_bpermute_b32 v72, v65, v71
	s_waitcnt lgkmcnt(2)
	v_add_f32_e32 v70, v70, v94
	v_fmamk_f32 v70, v70, 0x3a800000, v67
	v_mul_f32_e32 v75, 0x4b800000, v70
	v_cmp_gt_f32_e64 s[10:11], s22, v70
	s_waitcnt lgkmcnt(1)
	v_add_f32_e32 v69, v69, v93
	v_cndmask_b32_e64 v70, v70, v75, s[10:11]
	v_rsq_f32_e32 v75, v70
	ds_bpermute_b32 v70, v65, v69
	v_mul_f32_e32 v92, 0x45800000, v75
	v_cndmask_b32_e64 v92, v75, v92, s[10:11]
	v_pk_mul_f32 v[76:77], v[76:77], v[92:93] op_sel_hi:[1,0]
	v_pk_mul_f32 v[78:79], v[78:79], v[92:93] op_sel_hi:[1,0]
	v_cvt_pk_bf16_f32 v76, v76, v77
	v_cvt_pk_bf16_f32 v77, v78, v79
	global_store_dwordx2 v[58:59], v[76:77], off sc1
	v_pk_mul_f32 v[76:77], v[80:81], v[92:93] op_sel_hi:[1,0]
	v_pk_mul_f32 v[78:79], v[82:83], v[92:93] op_sel_hi:[1,0]
	v_cvt_pk_bf16_f32 v76, v76, v77
	v_cvt_pk_bf16_f32 v77, v78, v79
	global_store_dwordx2 v[58:59], v[76:77], off offset:512 sc1
	v_pk_mul_f32 v[76:77], v[84:85], v[92:93] op_sel_hi:[1,0]
	v_pk_mul_f32 v[78:79], v[86:87], v[92:93] op_sel_hi:[1,0]
	v_cvt_pk_bf16_f32 v76, v76, v77
	v_cvt_pk_bf16_f32 v77, v78, v79
	global_store_dwordx2 v[58:59], v[76:77], off offset:1024 sc1
	v_pk_mul_f32 v[76:77], v[88:89], v[92:93] op_sel_hi:[1,0]
	v_pk_mul_f32 v[78:79], v[90:91], v[92:93] op_sel_hi:[1,0]
	v_cvt_pk_bf16_f32 v76, v76, v77
	v_cvt_pk_bf16_f32 v77, v78, v79
	global_store_dwordx2 v[58:59], v[76:77], off offset:1536 sc1
	s_and_saveexec_b64 s[10:11], s[8:9]
	s_cbranch_execnz .LBB0_391
	s_or_b64 exec, exec, s[10:11]
	s_and_saveexec_b64 s[8:9], s[4:5]
	s_cbranch_execnz .LBB0_392

.LBB0_868:
	v_add_u32_e32 v0, s16, v58
	v_cmp_gt_i32_e64 s[6:7], s3, v0
	v_lshrrev_b32_e32 v69, 3, v58
	v_and_b32_e32 v59, 0x700, v66
	v_cndmask_b32_e64 v1, v58, v0, s[6:7]
	v_lshlrev_b32_e32 v2, 5, v1
	v_lshrrev_b32_e32 v3, 3, v1
	v_and_b32_e32 v2, 0x700, v2
	v_and_b32_e32 v3, 0xf8, v3
	v_and_b32_e32 v4, 0xfffff807, v1
	v_or3_b32 v2, v2, v4, v3
	v_cndmask_b32_e32 v56, v1, v2, vcc
	v_add_u32_e32 v2, s16, v0
	v_cmp_gt_i32_e64 s[0:1], s3, v2
	v_ashrrev_i32_e32 v57, 31, v56
	v_add_u32_e32 v68, s16, v2
	v_cndmask_b32_e64 v3, v58, v2, s[0:1]
	v_lshlrev_b32_e32 v0, 5, v3
	v_and_b32_e32 v4, 0x700, v0
	v_lshlrev_b64 v[0:1], 12, v[56:57]
	v_lshl_add_u64 v[0:1], v[50:51], 0, v[0:1]
	v_lshrrev_b32_e32 v5, 3, v3
	global_load_dwordx4 v[44:47], v[0:1], off sc1 nt
	global_load_dwordx4 v[40:43], v[0:1], off offset:1024 sc1 nt
	v_and_b32_e32 v5, 0xf8, v5
	v_and_b32_e32 v6, 0xfffff807, v3
	global_load_dwordx4 v[36:39], v[0:1], off offset:2048 sc1 nt
	global_load_dwordx4 v[32:35], v[0:1], off offset:3072 sc1 nt
	v_or3_b32 v0, v4, v6, v5
	v_cndmask_b32_e32 v54, v3, v0, vcc
	v_ashrrev_i32_e32 v55, 31, v54
	v_lshlrev_b64 v[0:1], 12, v[54:55]
	v_lshl_add_u64 v[0:1], v[50:51], 0, v[0:1]
	v_cmp_gt_i32_e64 s[4:5], s3, v68
	global_load_dwordx4 v[28:31], v[0:1], off sc1 nt
	global_load_dwordx4 v[24:27], v[0:1], off offset:1024 sc1 nt
	global_load_dwordx4 v[20:23], v[0:1], off offset:2048 sc1 nt
	global_load_dwordx4 v[16:19], v[0:1], off offset:3072 sc1 nt
	v_cndmask_b32_e64 v0, v58, v68, s[4:5]
	v_lshlrev_b32_e32 v1, 5, v0
	v_lshrrev_b32_e32 v2, 3, v0
	v_and_b32_e32 v3, 0xfffff807, v0
	v_and_b32_e32 v1, 0x700, v1
	v_and_b32_e32 v2, 0xf8, v2
	v_or3_b32 v1, v1, v3, v2
	v_cndmask_b32_e32 v52, v0, v1, vcc
	v_ashrrev_i32_e32 v53, 31, v52
	v_lshlrev_b64 v[0:1], 12, v[52:53]
	v_lshl_add_u64 v[0:1], v[50:51], 0, v[0:1]
	global_load_dwordx4 v[12:15], v[0:1], off sc1 nt
	global_load_dwordx4 v[8:11], v[0:1], off offset:1024 sc1 nt
	global_load_dwordx4 v[4:7], v[0:1], off offset:2048 sc1 nt
	s_nop 0
	global_load_dwordx4 v[0:3], v[0:1], off offset:3072 sc1 nt
	s_waitcnt lgkmcnt(0)
	v_and_b32_e32 v70, 0xfffff807, v58
	v_and_b32_e32 v69, 0xf8, v69
	v_or3_b32 v59, v59, v70, v69
	v_cndmask_b32_e32 v58, v58, v59, vcc
	v_ashrrev_i32_e32 v59, 31, v58
	v_lshlrev_b64 v[70:71], 12, v[58:59]
	v_lshl_add_u64 v[70:71], v[50:51], 0, v[70:71]
	global_load_dwordx4 v[76:79], v[70:71], off sc1 nt
	global_load_dwordx4 v[80:83], v[70:71], off offset:1024 sc1 nt
	global_load_dwordx4 v[84:87], v[70:71], off offset:2048 sc1 nt
	global_load_dwordx4 v[88:91], v[70:71], off offset:3072 sc1 nt
	v_lshlrev_b64 v[58:59], 11, v[58:59]
	v_lshl_add_u64 v[58:59], v[48:49], 0, v[58:59]
	s_waitcnt vmcnt(15)
	v_pk_mul_f32 v[70:71], v[44:45], v[44:45]
	s_waitcnt vmcnt(14)
	v_pk_mul_f32 v[74:75], v[40:41], v[40:41]
	v_pk_mul_f32 v[72:73], v[46:47], v[46:47]
	v_pk_mul_f32 v[92:93], v[42:43], v[42:43]
	s_waitcnt vmcnt(13)
	v_pk_mul_f32 v[94:95], v[36:37], v[36:37]
	v_add_f32_e32 v69, v74, v75
	v_add_f32_e32 v110, v70, v71
	v_pk_mul_f32 v[96:97], v[38:39], v[38:39]
	s_waitcnt vmcnt(12)
	v_pk_mul_f32 v[98:99], v[32:33], v[32:33]
	v_add_f32_e32 v111, v94, v95
	v_add_f32_e32 v69, v69, v92
	v_add_f32_e32 v72, v110, v72
	v_pk_mul_f32 v[100:101], v[34:35], v[34:35]
	v_add_f32_e32 v112, v98, v99
	v_add_f32_e32 v92, v111, v96
	v_add_f32_e32 v69, v69, v93
	v_add_f32_e32 v72, v72, v73
	v_add_f32_e32 v96, v112, v100
	v_add_f32_e32 v73, v92, v97
	v_add_f32_e32 v69, v72, v69
	v_add_f32_e32 v92, v96, v101
	v_add_f32_e32 v69, v69, v73
	s_waitcnt vmcnt(11)
	v_pk_mul_f32 v[70:71], v[28:29], v[28:29]
	s_waitcnt vmcnt(9)
	v_pk_mul_f32 v[102:103], v[20:21], v[20:21]
	v_add_f32_e32 v69, v69, v92
	v_add_f32_e32 v70, v70, v71
	v_add_f32_e32 v71, v102, v103
	ds_bpermute_b32 v103, v60, v69
	v_pk_mul_f32 v[74:75], v[30:31], v[30:31]
	v_pk_mul_f32 v[94:95], v[24:25], v[24:25]
	v_pk_mul_f32 v[98:99], v[26:27], v[26:27]
	v_add_f32_e32 v94, v94, v95
	v_add_f32_e32 v70, v70, v74
	v_pk_mul_f32 v[104:105], v[22:23], v[22:23]
	v_add_f32_e32 v72, v94, v98
	v_add_f32_e32 v70, v70, v75
	s_waitcnt vmcnt(6)
	v_pk_mul_f32 v[74:75], v[8:9], v[8:9]
	s_waitcnt lgkmcnt(0)
	v_add_f32_e32 v69, v69, v103
	v_add_f32_e32 v72, v72, v99
	v_add_f32_e32 v71, v71, v104
	v_add_f32_e32 v74, v74, v75
	ds_bpermute_b32 v75, v61, v69
	v_pk_mul_f32 v[106:107], v[16:17], v[16:17]
	v_add_f32_e32 v70, v70, v72
	v_add_f32_e32 v71, v71, v105
	v_pk_mul_f32 v[108:109], v[18:19], v[18:19]
	v_add_f32_e32 v70, v70, v71
	v_add_f32_e32 v71, v106, v107
	v_add_f32_e32 v71, v71, v108
	v_add_f32_e32 v71, v71, v109
	v_add_f32_e32 v102, v70, v71
	v_pk_mul_f32 v[70:71], v[12:13], v[12:13]
	s_waitcnt lgkmcnt(0)
	v_add_f32_e32 v69, v69, v75
	v_add_f32_e32 v70, v70, v71
	ds_bpermute_b32 v71, v62, v69
	v_pk_mul_f32 v[72:73], v[14:15], v[14:15]
	v_pk_mul_f32 v[92:93], v[10:11], v[10:11]
	s_waitcnt vmcnt(5)
	v_pk_mul_f32 v[94:95], v[4:5], v[4:5]
	v_pk_mul_f32 v[96:97], v[6:7], v[6:7]
	s_waitcnt lgkmcnt(0)
	v_add_f32_e32 v69, v69, v71
	v_add_f32_e32 v74, v74, v92
	v_add_f32_e32 v70, v70, v72
	v_add_f32_e32 v72, v94, v95
	ds_bpermute_b32 v71, v63, v69
	v_add_f32_e32 v74, v74, v93
	v_add_f32_e32 v70, v70, v73
	v_add_f32_e32 v72, v72, v96
	s_waitcnt vmcnt(4)
	v_pk_mul_f32 v[98:99], v[0:1], v[0:1]
	v_add_f32_e32 v70, v70, v74
	v_add_f32_e32 v72, v72, v97
	v_pk_mul_f32 v[100:101], v[2:3], v[2:3]
	v_add_f32_e32 v96, v70, v72
	v_add_f32_e32 v70, v98, v99
	s_waitcnt vmcnt(3)
	v_mov_b32_e32 v92, v77
	s_waitcnt vmcnt(2)
	v_mov_b32_e32 v93, v81
	v_add_f32_e32 v70, v70, v100
	v_mov_b32_e32 v74, v76
	v_mov_b32_e32 v75, v80
	v_pk_mul_f32 v[92:93], v[92:93], v[92:93]
	v_add_f32_e32 v97, v70, v101
	s_waitcnt lgkmcnt(0)
	v_add_f32_e32 v69, v69, v71
	v_mov_b32_e32 v70, v78
	v_mov_b32_e32 v71, v82
	v_pk_fma_f32 v[74:75], v[74:75], v[74:75], v[92:93]
	s_waitcnt vmcnt(1)
	v_mov_b32_e32 v94, v85
	s_waitcnt vmcnt(0)
	v_mov_b32_e32 v95, v89
	v_mov_b32_e32 v72, v79
	v_mov_b32_e32 v73, v83
	v_pk_fma_f32 v[70:71], v[70:71], v[70:71], v[74:75]
	v_mov_b32_e32 v92, v84
	v_mov_b32_e32 v93, v88
	v_pk_mul_f32 v[94:95], v[94:95], v[94:95]
	v_pk_fma_f32 v[70:71], v[72:73], v[72:73], v[70:71]
	v_mov_b32_e32 v72, v86
	v_mov_b32_e32 v73, v90
	v_pk_fma_f32 v[92:93], v[92:93], v[92:93], v[94:95]
	v_mov_b32_e32 v74, v87
	v_mov_b32_e32 v75, v91
	v_pk_fma_f32 v[72:73], v[72:73], v[72:73], v[92:93]
	v_add_f32_e32 v70, v70, v71
	v_pk_fma_f32 v[72:73], v[74:75], v[74:75], v[72:73]
	ds_bpermute_b32 v74, v60, v102
	v_add_f32_e32 v70, v70, v72
	v_add_f32_e32 v70, v70, v73
	ds_bpermute_b32 v71, v60, v70
	ds_bpermute_b32 v98, v64, v69
	s_waitcnt lgkmcnt(2)
	v_add_f32_e32 v74, v102, v74
	ds_bpermute_b32 v75, v61, v74
	v_add_f32_e32 v72, v96, v97
	s_waitcnt lgkmcnt(2)
	v_add_f32_e32 v70, v70, v71
	ds_bpermute_b32 v71, v61, v70
	s_waitcnt lgkmcnt(2)
	v_add_f32_e32 v73, v69, v98
	ds_bpermute_b32 v69, v60, v72
	s_waitcnt lgkmcnt(2)
	v_add_f32_e32 v74, v74, v75
	ds_bpermute_b32 v75, v62, v74
	s_waitcnt lgkmcnt(2)
	v_add_f32_e32 v70, v70, v71
	ds_bpermute_b32 v71, v62, v70
	s_waitcnt lgkmcnt(2)
	v_add_f32_e32 v69, v72, v69
	ds_bpermute_b32 v72, v61, v69
	s_waitcnt lgkmcnt(2)
	v_add_f32_e32 v74, v74, v75
	ds_bpermute_b32 v75, v63, v74
	s_waitcnt lgkmcnt(2)
	v_add_f32_e32 v70, v70, v71
	ds_bpermute_b32 v71, v63, v70
	s_waitcnt lgkmcnt(2)
	v_add_f32_e32 v69, v69, v72
	ds_bpermute_b32 v72, v62, v69
	s_waitcnt lgkmcnt(2)
	v_add_f32_e32 v75, v74, v75
	ds_bpermute_b32 v92, v64, v75
	s_waitcnt lgkmcnt(2)
	v_add_f32_e32 v70, v70, v71
	ds_bpermute_b32 v71, v64, v70
	s_waitcnt lgkmcnt(2)
	v_add_f32_e32 v69, v69, v72
	ds_bpermute_b32 v72, v63, v69
	ds_bpermute_b32 v74, v65, v73
	s_waitcnt lgkmcnt(2)
	v_add_f32_e32 v70, v70, v71
	ds_bpermute_b32 v94, v65, v70
	v_add_f32_e32 v71, v75, v92
	s_waitcnt lgkmcnt(2)
	v_add_f32_e32 v69, v69, v72
	ds_bpermute_b32 v93, v64, v69
	ds_bpermute_b32 v72, v65, v71
	s_waitcnt lgkmcnt(2)
	v_add_f32_e32 v70, v70, v94
	v_fmamk_f32 v70, v70, 0x3a800000, v67
	v_mul_f32_e32 v75, 0x4b800000, v70
	v_cmp_gt_f32_e64 s[8:9], s18, v70
	s_waitcnt lgkmcnt(1)
	v_add_f32_e32 v69, v69, v93
	v_cndmask_b32_e64 v70, v70, v75, s[8:9]
	v_rsq_f32_e32 v75, v70
	ds_bpermute_b32 v70, v65, v69
	v_mul_f32_e32 v92, 0x45800000, v75
	v_cndmask_b32_e64 v92, v75, v92, s[8:9]
	v_pk_mul_f32 v[76:77], v[76:77], v[92:93] op_sel_hi:[1,0]
	v_pk_mul_f32 v[78:79], v[78:79], v[92:93] op_sel_hi:[1,0]
	v_cvt_pk_bf16_f32 v76, v76, v77
	v_cvt_pk_bf16_f32 v77, v78, v79
	global_store_dwordx2 v[58:59], v[76:77], off sc1
	v_pk_mul_f32 v[76:77], v[80:81], v[92:93] op_sel_hi:[1,0]
	v_pk_mul_f32 v[78:79], v[82:83], v[92:93] op_sel_hi:[1,0]
	v_cvt_pk_bf16_f32 v76, v76, v77
	v_cvt_pk_bf16_f32 v77, v78, v79
	global_store_dwordx2 v[58:59], v[76:77], off offset:512 sc1
	v_pk_mul_f32 v[76:77], v[84:85], v[92:93] op_sel_hi:[1,0]
	v_pk_mul_f32 v[78:79], v[86:87], v[92:93] op_sel_hi:[1,0]
	v_cvt_pk_bf16_f32 v76, v76, v77
	v_cvt_pk_bf16_f32 v77, v78, v79
	global_store_dwordx2 v[58:59], v[76:77], off offset:1024 sc1
	v_pk_mul_f32 v[76:77], v[88:89], v[92:93] op_sel_hi:[1,0]
	v_pk_mul_f32 v[78:79], v[90:91], v[92:93] op_sel_hi:[1,0]
	v_cvt_pk_bf16_f32 v76, v76, v77
	v_cvt_pk_bf16_f32 v77, v78, v79
	global_store_dwordx2 v[58:59], v[76:77], off offset:1536 sc1
	s_and_saveexec_b64 s[8:9], s[6:7]
	s_cbranch_execnz .LBB0_871
	s_or_b64 exec, exec, s[8:9]
	s_and_saveexec_b64 s[6:7], s[0:1]
	s_cbranch_execnz .LBB0_872

.LBB0_1423:
	v_add_u32_e32 v0, s16, v58
	v_cmp_gt_i32_e64 s[6:7], s3, v0
	v_lshrrev_b32_e32 v69, 3, v58
	v_and_b32_e32 v59, 0x700, v66
	v_cndmask_b32_e64 v1, v58, v0, s[6:7]
	v_lshlrev_b32_e32 v2, 5, v1
	v_lshrrev_b32_e32 v3, 3, v1
	v_and_b32_e32 v2, 0x700, v2
	v_and_b32_e32 v3, 0xf8, v3
	v_and_b32_e32 v4, 0xfffff807, v1
	v_or3_b32 v2, v2, v4, v3
	v_cndmask_b32_e32 v56, v1, v2, vcc
	v_add_u32_e32 v2, s16, v0
	v_cmp_gt_i32_e64 s[0:1], s3, v2
	v_ashrrev_i32_e32 v57, 31, v56
	v_add_u32_e32 v68, s16, v2
	v_cndmask_b32_e64 v3, v58, v2, s[0:1]
	v_lshlrev_b32_e32 v0, 5, v3
	v_and_b32_e32 v4, 0x700, v0
	v_lshlrev_b64 v[0:1], 12, v[56:57]
	v_lshl_add_u64 v[0:1], v[50:51], 0, v[0:1]
	v_lshrrev_b32_e32 v5, 3, v3
	global_load_dwordx4 v[44:47], v[0:1], off sc1 nt
	global_load_dwordx4 v[40:43], v[0:1], off offset:1024 sc1 nt
	v_and_b32_e32 v5, 0xf8, v5
	v_and_b32_e32 v6, 0xfffff807, v3
	global_load_dwordx4 v[36:39], v[0:1], off offset:2048 sc1 nt
	global_load_dwordx4 v[32:35], v[0:1], off offset:3072 sc1 nt
	v_or3_b32 v0, v4, v6, v5
	v_cndmask_b32_e32 v54, v3, v0, vcc
	v_ashrrev_i32_e32 v55, 31, v54
	v_lshlrev_b64 v[0:1], 12, v[54:55]
	v_lshl_add_u64 v[0:1], v[50:51], 0, v[0:1]
	v_cmp_gt_i32_e64 s[4:5], s3, v68
	global_load_dwordx4 v[28:31], v[0:1], off sc1 nt
	global_load_dwordx4 v[24:27], v[0:1], off offset:1024 sc1 nt
	global_load_dwordx4 v[20:23], v[0:1], off offset:2048 sc1 nt
	global_load_dwordx4 v[16:19], v[0:1], off offset:3072 sc1 nt
	v_cndmask_b32_e64 v0, v58, v68, s[4:5]
	v_lshlrev_b32_e32 v1, 5, v0
	v_lshrrev_b32_e32 v2, 3, v0
	v_and_b32_e32 v3, 0xfffff807, v0
	v_and_b32_e32 v1, 0x700, v1
	v_and_b32_e32 v2, 0xf8, v2
	v_or3_b32 v1, v1, v3, v2
	v_cndmask_b32_e32 v52, v0, v1, vcc
	v_ashrrev_i32_e32 v53, 31, v52
	v_lshlrev_b64 v[0:1], 12, v[52:53]
	s_waitcnt lgkmcnt(0)
	v_lshl_add_u64 v[70:71], v[50:51], 0, v[0:1]
	global_load_dwordx4 v[12:15], v[70:71], off sc1 nt
	global_load_dwordx4 v[8:11], v[70:71], off offset:1024 sc1 nt
	global_load_dwordx4 v[4:7], v[70:71], off offset:2048 sc1 nt
	global_load_dwordx4 v[0:3], v[70:71], off offset:3072 sc1 nt
	v_and_b32_e32 v70, 0xfffff807, v58
	v_and_b32_e32 v69, 0xf8, v69
	v_or3_b32 v59, v59, v70, v69
	v_cndmask_b32_e32 v58, v58, v59, vcc
	v_ashrrev_i32_e32 v59, 31, v58
	v_lshlrev_b64 v[70:71], 12, v[58:59]
	v_lshl_add_u64 v[70:71], v[50:51], 0, v[70:71]
	global_load_dwordx4 v[76:79], v[70:71], off sc1 nt
	global_load_dwordx4 v[80:83], v[70:71], off offset:1024 sc1 nt
	global_load_dwordx4 v[84:87], v[70:71], off offset:2048 sc1 nt
	global_load_dwordx4 v[88:91], v[70:71], off offset:3072 sc1 nt
	v_lshlrev_b64 v[58:59], 11, v[58:59]
	v_lshl_add_u64 v[58:59], v[48:49], 0, v[58:59]
	s_waitcnt vmcnt(15)
	v_pk_mul_f32 v[70:71], v[44:45], v[44:45]
	s_waitcnt vmcnt(14)
	v_pk_mul_f32 v[74:75], v[40:41], v[40:41]
	v_pk_mul_f32 v[72:73], v[46:47], v[46:47]
	v_pk_mul_f32 v[92:93], v[42:43], v[42:43]
	s_waitcnt vmcnt(13)
	v_pk_mul_f32 v[94:95], v[36:37], v[36:37]
	v_add_f32_e32 v69, v74, v75
	v_add_f32_e32 v110, v70, v71
	v_pk_mul_f32 v[96:97], v[38:39], v[38:39]
	s_waitcnt vmcnt(12)
	v_pk_mul_f32 v[98:99], v[32:33], v[32:33]
	v_add_f32_e32 v111, v94, v95
	v_add_f32_e32 v69, v69, v92
	v_add_f32_e32 v72, v110, v72
	v_pk_mul_f32 v[100:101], v[34:35], v[34:35]
	v_add_f32_e32 v112, v98, v99
	v_add_f32_e32 v92, v111, v96
	v_add_f32_e32 v69, v69, v93
	v_add_f32_e32 v72, v72, v73
	v_add_f32_e32 v96, v112, v100
	v_add_f32_e32 v73, v92, v97
	v_add_f32_e32 v69, v72, v69
	v_add_f32_e32 v92, v96, v101
	v_add_f32_e32 v69, v69, v73
	s_waitcnt vmcnt(11)
	v_pk_mul_f32 v[70:71], v[28:29], v[28:29]
	s_waitcnt vmcnt(9)
	v_pk_mul_f32 v[102:103], v[20:21], v[20:21]
	v_add_f32_e32 v69, v69, v92
	v_add_f32_e32 v70, v70, v71
	v_add_f32_e32 v71, v102, v103
	ds_bpermute_b32 v103, v60, v69
	v_pk_mul_f32 v[74:75], v[30:31], v[30:31]
	v_pk_mul_f32 v[94:95], v[24:25], v[24:25]
	v_pk_mul_f32 v[98:99], v[26:27], v[26:27]
	v_add_f32_e32 v94, v94, v95
	v_add_f32_e32 v70, v70, v74
	v_pk_mul_f32 v[104:105], v[22:23], v[22:23]
	v_add_f32_e32 v72, v94, v98
	v_add_f32_e32 v70, v70, v75
	s_waitcnt vmcnt(6)
	v_pk_mul_f32 v[74:75], v[8:9], v[8:9]
	s_waitcnt lgkmcnt(0)
	v_add_f32_e32 v69, v69, v103
	v_add_f32_e32 v72, v72, v99
	v_add_f32_e32 v71, v71, v104
	v_add_f32_e32 v74, v74, v75
	ds_bpermute_b32 v75, v61, v69
	v_pk_mul_f32 v[106:107], v[16:17], v[16:17]
	v_add_f32_e32 v70, v70, v72
	v_add_f32_e32 v71, v71, v105
	v_pk_mul_f32 v[108:109], v[18:19], v[18:19]
	v_add_f32_e32 v70, v70, v71
	v_add_f32_e32 v71, v106, v107
	v_add_f32_e32 v71, v71, v108
	v_add_f32_e32 v71, v71, v109
	v_add_f32_e32 v102, v70, v71
	v_pk_mul_f32 v[70:71], v[12:13], v[12:13]
	s_waitcnt lgkmcnt(0)
	v_add_f32_e32 v69, v69, v75
	v_add_f32_e32 v70, v70, v71
	ds_bpermute_b32 v71, v62, v69
	v_pk_mul_f32 v[72:73], v[14:15], v[14:15]
	v_pk_mul_f32 v[92:93], v[10:11], v[10:11]
	s_waitcnt vmcnt(5)
	v_pk_mul_f32 v[94:95], v[4:5], v[4:5]
	v_pk_mul_f32 v[96:97], v[6:7], v[6:7]
	s_waitcnt lgkmcnt(0)
	v_add_f32_e32 v69, v69, v71
	v_add_f32_e32 v74, v74, v92
	v_add_f32_e32 v70, v70, v72
	v_add_f32_e32 v72, v94, v95
	ds_bpermute_b32 v71, v63, v69
	v_add_f32_e32 v74, v74, v93
	v_add_f32_e32 v70, v70, v73
	v_add_f32_e32 v72, v72, v96
	s_waitcnt vmcnt(4)
	v_pk_mul_f32 v[98:99], v[0:1], v[0:1]
	v_add_f32_e32 v70, v70, v74
	v_add_f32_e32 v72, v72, v97
	v_pk_mul_f32 v[100:101], v[2:3], v[2:3]
	v_add_f32_e32 v96, v70, v72
	v_add_f32_e32 v70, v98, v99
	s_waitcnt vmcnt(3)
	v_mov_b32_e32 v92, v77
	s_waitcnt vmcnt(2)
	v_mov_b32_e32 v93, v81
	v_add_f32_e32 v70, v70, v100
	v_mov_b32_e32 v74, v76
	v_mov_b32_e32 v75, v80
	v_pk_mul_f32 v[92:93], v[92:93], v[92:93]
	v_add_f32_e32 v97, v70, v101
	s_waitcnt lgkmcnt(0)
	v_add_f32_e32 v69, v69, v71
	v_mov_b32_e32 v70, v78
	v_mov_b32_e32 v71, v82
	v_pk_fma_f32 v[74:75], v[74:75], v[74:75], v[92:93]
	s_waitcnt vmcnt(1)
	v_mov_b32_e32 v94, v85
	s_waitcnt vmcnt(0)
	v_mov_b32_e32 v95, v89
	v_mov_b32_e32 v72, v79
	v_mov_b32_e32 v73, v83
	v_pk_fma_f32 v[70:71], v[70:71], v[70:71], v[74:75]
	v_mov_b32_e32 v92, v84
	v_mov_b32_e32 v93, v88
	v_pk_mul_f32 v[94:95], v[94:95], v[94:95]
	v_pk_fma_f32 v[70:71], v[72:73], v[72:73], v[70:71]
	v_mov_b32_e32 v72, v86
	v_mov_b32_e32 v73, v90
	v_pk_fma_f32 v[92:93], v[92:93], v[92:93], v[94:95]
	v_mov_b32_e32 v74, v87
	v_mov_b32_e32 v75, v91
	v_pk_fma_f32 v[72:73], v[72:73], v[72:73], v[92:93]
	v_add_f32_e32 v70, v70, v71
	v_pk_fma_f32 v[72:73], v[74:75], v[74:75], v[72:73]
	ds_bpermute_b32 v74, v60, v102
	v_add_f32_e32 v70, v70, v72
	v_add_f32_e32 v70, v70, v73
	ds_bpermute_b32 v71, v60, v70
	ds_bpermute_b32 v98, v64, v69
	s_waitcnt lgkmcnt(2)
	v_add_f32_e32 v74, v102, v74
	ds_bpermute_b32 v75, v61, v74
	v_add_f32_e32 v72, v96, v97
	s_waitcnt lgkmcnt(2)
	v_add_f32_e32 v70, v70, v71
	ds_bpermute_b32 v71, v61, v70
	s_waitcnt lgkmcnt(2)
	v_add_f32_e32 v73, v69, v98
	ds_bpermute_b32 v69, v60, v72
	s_waitcnt lgkmcnt(2)
	v_add_f32_e32 v74, v74, v75
	ds_bpermute_b32 v75, v62, v74
	s_waitcnt lgkmcnt(2)
	v_add_f32_e32 v70, v70, v71
	ds_bpermute_b32 v71, v62, v70
	s_waitcnt lgkmcnt(2)
	v_add_f32_e32 v69, v72, v69
	ds_bpermute_b32 v72, v61, v69
	s_waitcnt lgkmcnt(2)
	v_add_f32_e32 v74, v74, v75
	ds_bpermute_b32 v75, v63, v74
	s_waitcnt lgkmcnt(2)
	v_add_f32_e32 v70, v70, v71
	ds_bpermute_b32 v71, v63, v70
	s_waitcnt lgkmcnt(2)
	v_add_f32_e32 v69, v69, v72
	ds_bpermute_b32 v72, v62, v69
	s_waitcnt lgkmcnt(2)
	v_add_f32_e32 v75, v74, v75
	ds_bpermute_b32 v92, v64, v75
	s_waitcnt lgkmcnt(2)
	v_add_f32_e32 v70, v70, v71
	ds_bpermute_b32 v71, v64, v70
	s_waitcnt lgkmcnt(2)
	v_add_f32_e32 v69, v69, v72
	ds_bpermute_b32 v72, v63, v69
	ds_bpermute_b32 v74, v65, v73
	s_waitcnt lgkmcnt(2)
	v_add_f32_e32 v70, v70, v71
	ds_bpermute_b32 v94, v65, v70
	v_add_f32_e32 v71, v75, v92
	s_waitcnt lgkmcnt(2)
	v_add_f32_e32 v69, v69, v72
	ds_bpermute_b32 v93, v64, v69
	ds_bpermute_b32 v72, v65, v71
	s_waitcnt lgkmcnt(2)
	v_add_f32_e32 v70, v70, v94
	v_fmamk_f32 v70, v70, 0x3a800000, v67
	v_mul_f32_e32 v75, 0x4b800000, v70
	v_cmp_gt_f32_e64 s[8:9], s18, v70
	s_waitcnt lgkmcnt(1)
	v_add_f32_e32 v69, v69, v93
	v_cndmask_b32_e64 v70, v70, v75, s[8:9]
	v_rsq_f32_e32 v75, v70
	ds_bpermute_b32 v70, v65, v69
	v_mul_f32_e32 v92, 0x45800000, v75
	v_cndmask_b32_e64 v92, v75, v92, s[8:9]
	v_pk_mul_f32 v[76:77], v[76:77], v[92:93] op_sel_hi:[1,0]
	v_pk_mul_f32 v[78:79], v[78:79], v[92:93] op_sel_hi:[1,0]
	v_cvt_pk_bf16_f32 v76, v76, v77
	v_cvt_pk_bf16_f32 v77, v78, v79
	global_store_dwordx2 v[58:59], v[76:77], off sc1
	v_pk_mul_f32 v[76:77], v[80:81], v[92:93] op_sel_hi:[1,0]
	v_pk_mul_f32 v[78:79], v[82:83], v[92:93] op_sel_hi:[1,0]
	v_cvt_pk_bf16_f32 v76, v76, v77
	v_cvt_pk_bf16_f32 v77, v78, v79
	global_store_dwordx2 v[58:59], v[76:77], off offset:512 sc1
	v_pk_mul_f32 v[76:77], v[84:85], v[92:93] op_sel_hi:[1,0]
	v_pk_mul_f32 v[78:79], v[86:87], v[92:93] op_sel_hi:[1,0]
	v_cvt_pk_bf16_f32 v76, v76, v77
	v_cvt_pk_bf16_f32 v77, v78, v79
	global_store_dwordx2 v[58:59], v[76:77], off offset:1024 sc1
	v_pk_mul_f32 v[76:77], v[88:89], v[92:93] op_sel_hi:[1,0]
	v_pk_mul_f32 v[78:79], v[90:91], v[92:93] op_sel_hi:[1,0]
	v_cvt_pk_bf16_f32 v76, v76, v77
	v_cvt_pk_bf16_f32 v77, v78, v79
	global_store_dwordx2 v[58:59], v[76:77], off offset:1536 sc1
	s_and_saveexec_b64 s[8:9], s[6:7]
	s_cbranch_execnz .LBB0_1426
	s_or_b64 exec, exec, s[8:9]
	s_and_saveexec_b64 s[6:7], s[0:1]
	s_cbranch_execnz .LBB0_1427

.LBB0_1700:
	v_add_u32_e32 v17, s17, v72
	v_cmp_gt_i32_e64 s[6:7], s16, v17
	v_lshrrev_b32_e32 v83, 3, v72
	v_and_b32_e32 v73, 0x700, v80
	v_cndmask_b32_e64 v16, v72, v17, s[6:7]
	v_lshlrev_b32_e32 v18, 5, v16
	v_lshrrev_b32_e32 v19, 3, v16
	v_and_b32_e32 v18, 0x700, v18
	v_and_b32_e32 v19, 0xf8, v19
	v_and_b32_e32 v20, 0xfffff807, v16
	v_or3_b32 v18, v18, v20, v19
	v_cndmask_b32_e32 v16, v16, v18, vcc
	v_add_u32_e32 v18, s17, v17
	v_cmp_gt_i32_e64 s[4:5], s16, v18
	v_add_u32_e32 v82, s17, v18
	v_cmp_gt_i32_e64 s[0:1], s16, v82
	v_cndmask_b32_e64 v19, v72, v18, s[4:5]
	v_lshlrev_b32_e32 v17, 5, v19
	v_and_b32_e32 v20, 0x700, v17
	v_ashrrev_i32_e32 v17, 31, v16
	v_lshlrev_b64 v[16:17], 12, v[16:17]
	v_lshl_add_u64 v[70:71], v[64:65], 0, v[16:17]
	v_lshrrev_b32_e32 v16, 3, v19
	v_and_b32_e32 v16, 0xf8, v16
	v_and_b32_e32 v17, 0xfffff807, v19
	v_or3_b32 v16, v20, v17, v16
	v_cndmask_b32_e32 v16, v19, v16, vcc
	v_ashrrev_i32_e32 v17, 31, v16
	v_lshlrev_b64 v[16:17], 12, v[16:17]
	global_load_dwordx4 v[60:63], v[70:71], off sc1 nt
	global_load_dwordx4 v[56:59], v[70:71], off offset:1024 sc1 nt
	v_lshl_add_u64 v[68:69], v[64:65], 0, v[16:17]
	v_cndmask_b32_e64 v16, v72, v82, s[0:1]
	global_load_dwordx4 v[52:55], v[70:71], off offset:2048 sc1 nt
	v_lshlrev_b32_e32 v17, 5, v16
	v_lshrrev_b32_e32 v18, 3, v16
	global_load_dwordx4 v[48:51], v[70:71], off offset:3072 sc1 nt
	v_and_b32_e32 v19, 0xfffff807, v16
	v_and_b32_e32 v17, 0x700, v17
	v_and_b32_e32 v18, 0xf8, v18
	v_or3_b32 v17, v17, v19, v18
	v_cndmask_b32_e32 v16, v16, v17, vcc
	v_ashrrev_i32_e32 v17, 31, v16
	global_load_dwordx4 v[44:47], v[68:69], off sc1 nt
	global_load_dwordx4 v[40:43], v[68:69], off offset:1024 sc1 nt
	global_load_dwordx4 v[36:39], v[68:69], off offset:2048 sc1 nt
	global_load_dwordx4 v[32:35], v[68:69], off offset:3072 sc1 nt
	v_lshlrev_b64 v[16:17], 12, v[16:17]
	v_lshl_add_u64 v[66:67], v[64:65], 0, v[16:17]
	global_load_dwordx4 v[28:31], v[66:67], off sc1 nt
	global_load_dwordx4 v[24:27], v[66:67], off offset:1024 sc1 nt
	global_load_dwordx4 v[20:23], v[66:67], off offset:2048 sc1 nt
	global_load_dwordx4 v[16:19], v[66:67], off offset:3072 sc1 nt
	s_waitcnt lgkmcnt(0)
	v_and_b32_e32 v84, 0xfffff807, v72
	v_and_b32_e32 v83, 0xf8, v83
	v_or3_b32 v73, v73, v84, v83
	v_cndmask_b32_e32 v72, v72, v73, vcc
	v_ashrrev_i32_e32 v73, 31, v72
	v_lshlrev_b64 v[72:73], 12, v[72:73]
	v_lshl_add_u64 v[72:73], v[64:65], 0, v[72:73]
	global_load_dwordx4 v[90:93], v[72:73], off sc1 nt
	global_load_dwordx4 v[94:97], v[72:73], off offset:1024 sc1 nt
	global_load_dwordx4 v[98:101], v[72:73], off offset:2048 sc1 nt
	global_load_dwordx4 v[102:105], v[72:73], off offset:3072 sc1 nt
	s_waitcnt vmcnt(15)
	v_pk_mul_f32 v[84:85], v[60:61], v[60:61]
	s_waitcnt vmcnt(14)
	v_pk_mul_f32 v[88:89], v[56:57], v[56:57]
	v_pk_mul_f32 v[86:87], v[62:63], v[62:63]
	v_pk_mul_f32 v[106:107], v[58:59], v[58:59]
	s_waitcnt vmcnt(13)
	v_pk_mul_f32 v[108:109], v[52:53], v[52:53]
	v_add_f32_e32 v83, v88, v89
	v_add_f32_e32 v124, v84, v85
	v_pk_mul_f32 v[110:111], v[54:55], v[54:55]
	s_waitcnt vmcnt(12)
	v_pk_mul_f32 v[112:113], v[48:49], v[48:49]
	v_add_f32_e32 v125, v108, v109
	v_add_f32_e32 v83, v83, v106
	v_add_f32_e32 v86, v124, v86
	v_pk_mul_f32 v[114:115], v[50:51], v[50:51]
	v_add_f32_e32 v126, v112, v113
	s_waitcnt vmcnt(11)
	v_pk_mul_f32 v[84:85], v[44:45], v[44:45]
	v_add_f32_e32 v106, v125, v110
	v_add_f32_e32 v83, v83, v107
	v_add_f32_e32 v86, v86, v87
	v_pk_mul_f32 v[88:89], v[46:47], v[46:47]
	s_waitcnt vmcnt(10)
	v_pk_mul_f32 v[108:109], v[40:41], v[40:41]
	v_add_f32_e32 v110, v126, v114
	v_add_f32_e32 v87, v106, v111
	v_add_f32_e32 v83, v86, v83
	v_add_f32_e32 v84, v84, v85
	v_pk_mul_f32 v[112:113], v[42:43], v[42:43]
	s_waitcnt vmcnt(9)
	v_pk_mul_f32 v[116:117], v[36:37], v[36:37]
	v_add_f32_e32 v108, v108, v109
	v_add_f32_e32 v106, v110, v115
	v_add_f32_e32 v83, v83, v87
	v_add_f32_e32 v84, v84, v88
	v_pk_mul_f32 v[118:119], v[38:39], v[38:39]
	v_add_f32_e32 v83, v83, v106
	v_add_f32_e32 v86, v108, v112
	v_add_f32_e32 v84, v84, v89
	v_add_f32_e32 v85, v116, v117
	s_waitcnt vmcnt(6)
	v_pk_mul_f32 v[88:89], v[24:25], v[24:25]
	v_add_f32_e32 v86, v86, v113
	v_add_f32_e32 v85, v85, v118
	v_add_f32_e32 v88, v88, v89
	ds_bpermute_b32 v89, v74, v83
	v_pk_mul_f32 v[120:121], v[32:33], v[32:33]
	v_add_f32_e32 v84, v84, v86
	v_add_f32_e32 v85, v85, v119
	v_pk_mul_f32 v[122:123], v[34:35], v[34:35]
	v_add_f32_e32 v84, v84, v85
	v_add_f32_e32 v85, v120, v121
	v_add_f32_e32 v85, v85, v122
	v_add_f32_e32 v85, v85, v123
	v_add_f32_e32 v116, v84, v85
	v_pk_mul_f32 v[84:85], v[28:29], v[28:29]
	s_waitcnt lgkmcnt(0)
	v_add_f32_e32 v83, v83, v89
	v_add_f32_e32 v84, v84, v85
	ds_bpermute_b32 v85, v75, v83
	v_pk_mul_f32 v[86:87], v[30:31], v[30:31]
	v_pk_mul_f32 v[106:107], v[26:27], v[26:27]
	s_waitcnt vmcnt(5)
	v_pk_mul_f32 v[108:109], v[20:21], v[20:21]
	v_pk_mul_f32 v[110:111], v[22:23], v[22:23]
	s_waitcnt lgkmcnt(0)
	v_add_f32_e32 v83, v83, v85
	v_add_f32_e32 v88, v88, v106
	v_add_f32_e32 v84, v84, v86
	v_add_f32_e32 v86, v108, v109
	ds_bpermute_b32 v85, v76, v83
	v_add_f32_e32 v88, v88, v107
	v_add_f32_e32 v84, v84, v87
	v_add_f32_e32 v86, v86, v110
	s_waitcnt vmcnt(4)
	v_pk_mul_f32 v[112:113], v[16:17], v[16:17]
	v_add_f32_e32 v84, v84, v88
	v_add_f32_e32 v86, v86, v111
	v_pk_mul_f32 v[114:115], v[18:19], v[18:19]
	v_add_f32_e32 v108, v84, v86
	v_add_f32_e32 v84, v112, v113
	v_add_f32_e32 v84, v84, v114
	s_waitcnt vmcnt(3)
	v_mov_b32_e32 v86, v91
	s_waitcnt vmcnt(2)
	v_mov_b32_e32 v87, v95
	v_add_f32_e32 v109, v84, v115
	s_waitcnt lgkmcnt(0)
	v_add_f32_e32 v83, v83, v85
	v_mov_b32_e32 v84, v90
	v_mov_b32_e32 v85, v94
	v_pk_mul_f32 v[86:87], v[86:87], v[86:87]
	v_mov_b32_e32 v88, v93
	v_pk_fma_f32 v[84:85], v[84:85], v[84:85], v[86:87]
	v_mov_b32_e32 v86, v92
	v_mov_b32_e32 v87, v96
	v_mov_b32_e32 v89, v97
	v_pk_fma_f32 v[84:85], v[86:87], v[86:87], v[84:85]
	s_waitcnt vmcnt(1)
	v_mov_b32_e32 v86, v98
	v_pk_fma_f32 v[84:85], v[88:89], v[88:89], v[84:85]
	v_mov_b32_e32 v88, v99
	s_waitcnt vmcnt(0)
	v_mov_b32_e32 v89, v103
	v_mov_b32_e32 v87, v102
	v_pk_mul_f32 v[88:89], v[88:89], v[88:89]
	v_mov_b32_e32 v106, v101
	v_pk_fma_f32 v[86:87], v[86:87], v[86:87], v[88:89]
	v_mov_b32_e32 v88, v100
	v_mov_b32_e32 v89, v104
	v_mov_b32_e32 v107, v105
	v_pk_fma_f32 v[86:87], v[88:89], v[88:89], v[86:87]
	v_add_f32_e32 v84, v84, v85
	v_pk_fma_f32 v[86:87], v[106:107], v[106:107], v[86:87]
	ds_bpermute_b32 v110, v77, v83
	v_add_f32_e32 v84, v84, v86
	v_add_f32_e32 v84, v84, v87
	ds_bpermute_b32 v85, v74, v84
	ds_bpermute_b32 v87, v74, v116
	s_waitcnt lgkmcnt(2)
	v_add_f32_e32 v83, v83, v110
	ds_bpermute_b32 v88, v78, v83
	v_add_f32_e32 v86, v108, v109
	s_waitcnt lgkmcnt(2)
	v_add_f32_e32 v84, v84, v85
	ds_bpermute_b32 v85, v75, v84
	s_waitcnt lgkmcnt(2)
	v_add_f32_e32 v89, v116, v87
	s_waitcnt lgkmcnt(1)
	v_add_f32_e32 v87, v83, v88
	ds_bpermute_b32 v83, v74, v86
	ds_bpermute_b32 v106, v75, v89
	s_waitcnt lgkmcnt(2)
	v_add_f32_e32 v84, v84, v85
	ds_bpermute_b32 v85, v76, v84
	s_waitcnt lgkmcnt(2)
	v_add_f32_e32 v83, v86, v83
	s_waitcnt lgkmcnt(1)
	v_add_f32_e32 v88, v89, v106
	ds_bpermute_b32 v86, v75, v83
	s_waitcnt lgkmcnt(1)
	v_add_f32_e32 v84, v84, v85
	ds_bpermute_b32 v85, v77, v84
	ds_bpermute_b32 v89, v76, v88
	s_waitcnt lgkmcnt(2)
	v_add_f32_e32 v83, v83, v86
	ds_bpermute_b32 v86, v76, v83
	s_waitcnt lgkmcnt(2)
	v_add_f32_e32 v84, v84, v85
	ds_bpermute_b32 v85, v78, v84
	s_waitcnt lgkmcnt(2)
	v_add_f32_e32 v88, v88, v89
	ds_bpermute_b32 v89, v77, v88
	s_waitcnt lgkmcnt(2)
	v_add_f32_e32 v83, v83, v86
	ds_bpermute_b32 v86, v77, v83
	s_waitcnt lgkmcnt(2)
	v_add_f32_e32 v84, v84, v85
	ds_bpermute_b32 v107, v79, v84
	s_waitcnt lgkmcnt(2)
	v_add_f32_e32 v89, v88, v89
	ds_bpermute_b32 v106, v78, v89
	s_waitcnt lgkmcnt(2)
	v_add_f32_e32 v83, v83, v86
	ds_bpermute_b32 v88, v79, v87
	s_waitcnt lgkmcnt(2)
	v_add_f32_e32 v84, v84, v107
	v_fmamk_f32 v84, v84, 0x3a800000, v81
	v_mul_f32_e32 v86, 0x4b800000, v84
	v_cmp_gt_f32_e64 s[2:3], s19, v84
	s_waitcnt lgkmcnt(1)
	v_add_f32_e32 v85, v89, v106
	ds_bpermute_b32 v89, v78, v83
	v_cndmask_b32_e64 v84, v84, v86, s[2:3]
	v_rsq_f32_e32 v106, v84
	ds_bpermute_b32 v86, v79, v85
	s_waitcnt lgkmcnt(1)
	v_add_f32_e32 v83, v83, v89
	v_mul_f32_e32 v89, 0x45800000, v106
	v_cndmask_b32_e64 v106, v106, v89, s[2:3]
	v_pk_mul_f32 v[90:91], v[90:91], v[106:107] op_sel_hi:[1,0]
	v_pk_mul_f32 v[92:93], v[92:93], v[106:107] op_sel_hi:[1,0]
	v_pk_mul_f32 v[90:91], v[0:1], v[90:91]
	v_pk_mul_f32 v[92:93], v[2:3], v[92:93]
	global_store_dwordx4 v[72:73], v[90:93], off sc1
	ds_bpermute_b32 v84, v79, v83
	s_nop 0
	v_pk_mul_f32 v[90:91], v[94:95], v[106:107] op_sel_hi:[1,0]
	v_pk_mul_f32 v[92:93], v[96:97], v[106:107] op_sel_hi:[1,0]
	v_pk_mul_f32 v[90:91], v[4:5], v[90:91]
	v_pk_mul_f32 v[92:93], v[6:7], v[92:93]
	global_store_dwordx4 v[72:73], v[90:93], off offset:1024 sc1
	s_nop 1
	v_pk_mul_f32 v[90:91], v[98:99], v[106:107] op_sel_hi:[1,0]
	v_pk_mul_f32 v[92:93], v[100:101], v[106:107] op_sel_hi:[1,0]
	v_pk_mul_f32 v[90:91], v[8:9], v[90:91]
	v_pk_mul_f32 v[92:93], v[10:11], v[92:93]
	global_store_dwordx4 v[72:73], v[90:93], off offset:2048 sc1
	s_nop 1
	v_pk_mul_f32 v[90:91], v[102:103], v[106:107] op_sel_hi:[1,0]
	v_pk_mul_f32 v[92:93], v[104:105], v[106:107] op_sel_hi:[1,0]
	v_pk_mul_f32 v[90:91], v[12:13], v[90:91]
	v_pk_mul_f32 v[92:93], v[14:15], v[92:93]
	global_store_dwordx4 v[72:73], v[90:93], off offset:3072 sc1
	s_and_saveexec_b64 s[14:15], s[6:7]
	s_cbranch_execnz .LBB0_1703
	s_or_b64 exec, exec, s[14:15]
	s_and_saveexec_b64 s[6:7], s[4:5]
	s_cbranch_execnz .LBB0_1704
